# plus: FoX steady attention loop hand-scheduled the same way (mid-step barrier, prefetched K/V/forget-bias fragments, softmax under the MFMAs)
# speedup vs baseline: 1.0101x; 1.0076x over previous
.LBB0_654:
	v_lshlrev_b32_e32 v16, 3, v18
	v_lshrrev_b32_e32 v14, 2, v19
	v_lshlrev_b32_e32 v15, 1, v18
	v_and_b32_e32 v16, 24, v16
	v_and_or_b32 v15, v15, 32, v16
	v_and_or_b32 v14, v14, 3, v156
	v_lshl_or_b32 v14, v14, 6, v15
	v_lshl_add_u64 v[136:137], v[12:13], 1, s[12:13]
	s_add_i32 s12, s10, 2
	v_mul_u32_u24_e32 v164, 0x90, v20
	v_lshl_add_u64 v[138:139], v[144:145], 1, s[14:15]
	s_cmp_ge_i32 s12, s35
	v_add_u32_e32 v158, 0, v30
	v_add_u32_e32 v159, 0, v14
	s_barrier
	s_cbranch_scc1 .LBB0_669
	v_add_u32_e32 v218, v164, v30
	v_mov_b32_e32 v14, 0
	v_mov_b32_e32 v15, 0
	v_mov_b32_e32 v16, 0
	v_mov_b32_e32 v17, 0
	v_mov_b32_e32 v18, 0
	v_mov_b32_e32 v19, 0
	v_mov_b32_e32 v20, 0
	v_mov_b32_e32 v21, 0
	v_mov_b32_e32 v22, 0
	v_mov_b32_e32 v23, 0
	v_mov_b32_e32 v24, 0
	v_mov_b32_e32 v25, 0
	v_mov_b32_e32 v26, 0
	v_mov_b32_e32 v27, 0
	v_mov_b32_e32 v28, 0
	v_mov_b32_e32 v29, 0
	v_mov_b32_e32 v30, 0
	v_mov_b32_e32 v31, 0
	v_mov_b32_e32 v32, 0
	v_mov_b32_e32 v33, 0
	v_mov_b32_e32 v34, 0
	v_mov_b32_e32 v35, 0
	v_mov_b32_e32 v36, 0
	v_mov_b32_e32 v37, 0
	v_mov_b32_e32 v38, 0
	v_mov_b32_e32 v39, 0
	v_mov_b32_e32 v40, 0
	v_mov_b32_e32 v41, 0
	v_mov_b32_e32 v42, 0
	v_mov_b32_e32 v43, 0
	v_mov_b32_e32 v44, 0
	v_mov_b32_e32 v45, 0
	v_mov_b32_e32 v161, 0
	v_mov_b32_e32 v160, 0xf149f2ca
	s_add_i32 s12, s10, 2
	s_ashr_i32 s13, s12, 31
	s_lshl_b64 s[14:15], s[12:13], 16
	v_lshl_add_u64 v[244:245], v[136:137], 0, s[14:15]
	s_lshl_b64 s[14:15], s[12:13], 8
	v_mov_b32_e32 v141, 0
	v_lshl_add_u64 v[250:251], s[4:5], 0, v[140:141]
	v_lshl_add_u64 v[250:251], v[250:251], 0, s[14:15]
	s_add_i32 s12, s10, 1
	s_ashr_i32 s13, s12, 31
	s_lshl_b64 s[14:15], s[12:13], 16
	v_lshl_add_u64 v[248:249], v[138:139], 0, s[14:15]
	global_load_dwordx4 v[114:117], v[244:245], off
	s_and_saveexec_b64 s[12:13], s[6:7]
	s_cbranch_execz .Lfox_nockp
	global_load_dword v152, v[250:251], off
.Lfox_nockp:
	s_or_b64 exec, exec, s[12:13]
	global_load_dwordx4 v[118:121], v[248:249], off
	s_mov_b64 s[14:15], 0x10000
	v_lshl_add_u64 v[242:243], v[244:245], 0, s[14:15]
	v_lshl_add_u64 v[244:245], v[242:243], 0, s[14:15]
	v_lshl_add_u64 v[246:247], v[248:249], 0, s[14:15]
	v_lshl_add_u64 v[248:249], v[246:247], 0, s[14:15]
	s_mov_b64 s[14:15], 0x100
	v_lshl_add_u64 v[250:251], v[250:251], 0, s[14:15]
	ds_read_b128 v[78:81], v158 offset:43264
	ds_read_b128 v[82:85], v158 offset:43296
	ds_read_b128 v[86:89], v158 offset:43328
	ds_read_b128 v[90:93], v158 offset:43360
	ds_read_b128 v[94:97], v158 offset:43392
	ds_read_b128 v[98:101], v158 offset:43424
	ds_read_b128 v[102:105], v158 offset:43456
	ds_read_b128 v[106:109], v158 offset:43488
	s_waitcnt lgkmcnt(4)
	ds_read_b128 v[190:193], v218 offset:13312
	ds_read_b128 v[194:197], v218 offset:17920
	ds_read_b128 v[198:201], v218 offset:13344
	ds_read_b128 v[202:205], v218 offset:17952
	ds_read_b128 v[206:209], v218 offset:13376
	ds_read_b128 v[210:213], v218 offset:17984
	ds_read_b128 v[214:217], v218 offset:13408
	ds_read_b128 v[222:225], v218 offset:18016
	v_max3_f32 v124, v46, v47, v48
	v_max3_f32 v125, v49, v50, v51
	v_max3_f32 v124, v124, v52, v53
	v_max3_f32 v125, v125, v54, v55
	v_max3_f32 v124, v124, v56, v57
	v_max3_f32 v125, v125, v58, v59
	v_max3_f32 v124, v124, v60, v61
	v_max3_f32 v125, v125, v62, v63
	v_max3_f32 v124, v124, v64, v65
	v_max3_f32 v125, v125, v66, v67
	v_max3_f32 v124, v124, v68, v69
	v_max3_f32 v125, v125, v70, v71
	v_max3_f32 v124, v124, v72, v73
	v_max3_f32 v125, v125, v74, v75
	v_max3_f32 v124, v124, v76, v77
	v_max_f32_e32 v124, v124, v125
	v_mov_b32_e32 v125, v124
	s_nop 1
	v_permlane32_swap_b32_e32 v124, v125
	v_max_f32_e32 v126, v124, v125
.Lfox_loop:
	v_add_f32_e32 v127, 0x41800000, v160
	v_cmp_gt_f32_e32 vcc, v126, v127
	s_cbranch_vccnz .Lfox_resc0
.Lfox_resc_ret0:
	s_waitcnt lgkmcnt(7)
	v_mfma_f32_32x32x16_bf16 v[78:93], v[190:193], v[0:3], v[78:93]
	ds_read_b64_tr_b16 v[190:191], v159 offset:26624
	ds_read_b64_tr_b16 v[192:193], v159 offset:27136
	v_sub_f32_e32 v46, v46, v160
	v_sub_f32_e32 v47, v47, v160
	v_sub_f32_e32 v48, v48, v160
	v_sub_f32_e32 v49, v49, v160
	v_sub_f32_e32 v50, v50, v160
	v_sub_f32_e32 v51, v51, v160
	v_sub_f32_e32 v52, v52, v160
	v_sub_f32_e32 v53, v53, v160
	v_exp_f32_e32 v46, v46
	v_exp_f32_e32 v47, v47
	v_exp_f32_e32 v48, v48
	v_exp_f32_e32 v49, v49
	s_waitcnt lgkmcnt(8)
	v_mfma_f32_32x32x16_bf16 v[94:109], v[194:197], v[0:3], v[94:109]
	ds_read_b64_tr_b16 v[194:195], v159 offset:30720
	ds_read_b64_tr_b16 v[196:197], v159 offset:31232
	v_exp_f32_e32 v50, v50
	v_exp_f32_e32 v51, v51
	v_exp_f32_e32 v52, v52
	v_exp_f32_e32 v53, v53
	v_add_f32_e32 v122, v46, v47
	v_add_f32_e32 v123, v48, v49
	v_add_f32_e32 v122, v122, v50
	v_add_f32_e32 v123, v123, v51
	v_add_f32_e32 v122, v122, v52
	v_add_f32_e32 v123, v123, v53
	v_cvt_pk_bf16_f32 v226, v46, v47
	v_cvt_pk_bf16_f32 v227, v48, v49
	s_waitcnt lgkmcnt(9)
	v_mfma_f32_32x32x16_bf16 v[78:93], v[198:201], v[4:7], v[78:93]
	ds_read_b64_tr_b16 v[198:199], v159 offset:27648
	ds_read_b64_tr_b16 v[200:201], v159 offset:28160
	v_cvt_pk_bf16_f32 v228, v50, v51
	v_cvt_pk_bf16_f32 v229, v52, v53
	v_sub_f32_e32 v54, v54, v160
	v_sub_f32_e32 v55, v55, v160
	v_sub_f32_e32 v56, v56, v160
	v_sub_f32_e32 v57, v57, v160
	v_sub_f32_e32 v58, v58, v160
	v_sub_f32_e32 v59, v59, v160
	v_sub_f32_e32 v60, v60, v160
	v_sub_f32_e32 v61, v61, v160
	v_exp_f32_e32 v54, v54
	s_waitcnt lgkmcnt(10)
	v_mfma_f32_32x32x16_bf16 v[94:109], v[202:205], v[4:7], v[94:109]
	ds_read_b64_tr_b16 v[202:203], v159 offset:31744
	ds_read_b64_tr_b16 v[204:205], v159 offset:32256
	v_exp_f32_e32 v55, v55
	v_exp_f32_e32 v56, v56
	v_exp_f32_e32 v57, v57
	v_exp_f32_e32 v58, v58
	v_exp_f32_e32 v59, v59
	v_exp_f32_e32 v60, v60
	v_exp_f32_e32 v61, v61
	v_add_f32_e32 v122, v122, v54
	v_add_f32_e32 v123, v123, v55
	v_add_f32_e32 v122, v122, v56
	v_add_f32_e32 v123, v123, v57
	s_waitcnt lgkmcnt(11)
	v_mfma_f32_32x32x16_bf16 v[78:93], v[206:209], v[8:11], v[78:93]
	ds_read_b64_tr_b16 v[206:207], v159 offset:28672
	ds_read_b64_tr_b16 v[208:209], v159 offset:29184
	v_add_f32_e32 v122, v122, v58
	v_add_f32_e32 v123, v123, v59
	v_add_f32_e32 v122, v122, v60
	v_add_f32_e32 v123, v123, v61
	v_cvt_pk_bf16_f32 v230, v54, v55
	v_cvt_pk_bf16_f32 v231, v56, v57
	v_cvt_pk_bf16_f32 v232, v58, v59
	v_cvt_pk_bf16_f32 v233, v60, v61
	v_sub_f32_e32 v62, v62, v160
	v_sub_f32_e32 v63, v63, v160
	v_sub_f32_e32 v64, v64, v160
	s_waitcnt lgkmcnt(12)
	v_mfma_f32_32x32x16_bf16 v[94:109], v[210:213], v[8:11], v[94:109]
	ds_read_b64_tr_b16 v[210:211], v159 offset:32768
	ds_read_b64_tr_b16 v[212:213], v159 offset:33280
	v_sub_f32_e32 v65, v65, v160
	v_sub_f32_e32 v66, v66, v160
	v_sub_f32_e32 v67, v67, v160
	v_sub_f32_e32 v68, v68, v160
	v_sub_f32_e32 v69, v69, v160
	v_exp_f32_e32 v62, v62
	v_exp_f32_e32 v63, v63
	v_exp_f32_e32 v64, v64
	v_exp_f32_e32 v65, v65
	v_exp_f32_e32 v66, v66
	v_exp_f32_e32 v67, v67
	s_waitcnt lgkmcnt(13)
	v_mfma_f32_32x32x16_bf16 v[78:93], v[214:217], v[110:113], v[78:93]
	ds_read_b64_tr_b16 v[214:215], v159 offset:29696
	ds_read_b64_tr_b16 v[216:217], v159 offset:30208
	v_exp_f32_e32 v68, v68
	v_exp_f32_e32 v69, v69
	v_add_f32_e32 v122, v122, v62
	v_add_f32_e32 v123, v123, v63
	v_add_f32_e32 v122, v122, v64
	v_add_f32_e32 v123, v123, v65
	v_add_f32_e32 v122, v122, v66
	v_add_f32_e32 v123, v123, v67
	v_add_f32_e32 v122, v122, v68
	v_add_f32_e32 v123, v123, v69
	v_cvt_pk_bf16_f32 v234, v62, v63
	s_waitcnt lgkmcnt(14)
	v_mfma_f32_32x32x16_bf16 v[94:109], v[222:225], v[110:113], v[94:109]
	s_waitcnt lgkmcnt(13)
	ds_read_b64_tr_b16 v[222:223], v159 offset:33792
	ds_read_b64_tr_b16 v[224:225], v159 offset:34304
	v_cvt_pk_bf16_f32 v235, v64, v65
	v_cvt_pk_bf16_f32 v236, v66, v67
	v_cvt_pk_bf16_f32 v237, v68, v69
	v_sub_f32_e32 v70, v70, v160
	v_sub_f32_e32 v71, v71, v160
	v_sub_f32_e32 v72, v72, v160
	v_sub_f32_e32 v73, v73, v160
	v_sub_f32_e32 v74, v74, v160
	v_sub_f32_e32 v75, v75, v160
	v_sub_f32_e32 v76, v76, v160
	v_sub_f32_e32 v77, v77, v160
	s_waitcnt lgkmcnt(8)
	s_waitcnt vmcnt(0)
	ds_write_b128 v162, v[114:117]
	s_and_saveexec_b64 s[12:13], s[6:7]
	s_cbranch_execz .Lfox_nocw0
	v_xor_b32_e32 v152, 0x80000000, v152
	ds_write_b32 v154, v152 offset:43008
.Lfox_nocw0:
	s_or_b64 exec, exec, s[12:13]
	ds_write_b128 v155, v[118:121] offset:34816
	v_exp_f32_e32 v70, v70
	v_exp_f32_e32 v71, v71
	v_exp_f32_e32 v72, v72
	v_exp_f32_e32 v73, v73
	v_exp_f32_e32 v74, v74
	v_exp_f32_e32 v75, v75
	v_exp_f32_e32 v76, v76
	v_exp_f32_e32 v77, v77
	v_add_f32_e32 v122, v122, v70
	v_add_f32_e32 v123, v123, v71
	v_add_f32_e32 v122, v122, v72
	v_add_f32_e32 v123, v123, v73
	v_add_f32_e32 v122, v122, v74
	v_add_f32_e32 v123, v123, v75
	v_add_f32_e32 v122, v122, v76
	v_add_f32_e32 v123, v123, v77
	v_cvt_pk_bf16_f32 v238, v70, v71
	v_cvt_pk_bf16_f32 v239, v72, v73
	v_cvt_pk_bf16_f32 v240, v74, v75
	v_cvt_pk_bf16_f32 v241, v76, v77
	v_add_f32_e32 v122, v122, v123
	v_add_f32_e32 v161, v161, v122
	s_waitcnt lgkmcnt(0)
	s_barrier
	ds_read_b128 v[46:49], v158 offset:43008
	ds_read_b128 v[50:53], v158 offset:43040
	ds_read_b128 v[54:57], v158 offset:43072
	ds_read_b128 v[58:61], v158 offset:43104
	ds_read_b128 v[62:65], v158 offset:43136
	ds_read_b128 v[66:69], v158 offset:43168
	ds_read_b128 v[70:73], v158 offset:43200
	ds_read_b128 v[74:77], v158 offset:43232
	v_mfma_f32_32x32x16_bf16 v[14:29], v[190:193], v[226:229], v[14:29]
	ds_read_b128 v[190:193], v218
	v_max3_f32 v124, v78, v79, v80
	v_max3_f32 v125, v81, v82, v83
	v_max3_f32 v124, v124, v84, v85
	v_mfma_f32_32x32x16_bf16 v[30:45], v[194:197], v[226:229], v[30:45]
	ds_read_b128 v[194:197], v218 offset:4608
	global_load_dwordx4 v[114:117], v[242:243], off
	s_and_saveexec_b64 s[12:13], s[6:7]
	s_cbranch_execz .Lfox_nock0
	global_load_dword v152, v[250:251], off
.Lfox_nock0:
	s_or_b64 exec, exec, s[12:13]
	global_load_dwordx4 v[118:121], v[246:247], off
	v_max3_f32 v125, v125, v86, v87
	v_max3_f32 v124, v124, v88, v89
	v_max3_f32 v125, v125, v90, v91
	v_mfma_f32_32x32x16_bf16 v[14:29], v[198:201], v[230:233], v[14:29]
	ds_read_b128 v[198:201], v218 offset:32
	v_max3_f32 v124, v124, v92, v93
	v_max3_f32 v125, v125, v94, v95
	v_max3_f32 v124, v124, v96, v97
	v_mfma_f32_32x32x16_bf16 v[30:45], v[202:205], v[230:233], v[30:45]
	ds_read_b128 v[202:205], v218 offset:4640
	v_max3_f32 v125, v125, v98, v99
	v_max3_f32 v124, v124, v100, v101
	v_max3_f32 v125, v125, v102, v103
	v_mfma_f32_32x32x16_bf16 v[14:29], v[206:209], v[234:237], v[14:29]
	ds_read_b128 v[206:209], v218 offset:64
	v_max3_f32 v124, v124, v104, v105
	v_max3_f32 v125, v125, v106, v107
	v_mfma_f32_32x32x16_bf16 v[30:45], v[210:213], v[234:237], v[30:45]
	ds_read_b128 v[210:213], v218 offset:4672
	v_max3_f32 v124, v124, v108, v109
	v_max_f32_e32 v124, v124, v125
	v_mfma_f32_32x32x16_bf16 v[14:29], v[214:217], v[238:241], v[14:29]
	ds_read_b128 v[214:217], v218 offset:96
	v_mov_b32_e32 v125, v124
	s_nop 1
	v_mfma_f32_32x32x16_bf16 v[30:45], v[222:225], v[238:241], v[30:45]
	s_waitcnt lgkmcnt(14)
	ds_read_b128 v[222:225], v218 offset:4704
	v_permlane32_swap_b32_e32 v124, v125
	v_max_f32_e32 v126, v124, v125
	v_lshl_add_u64 v[242:243], v[242:243], 0, s[46:47]
	v_lshl_add_u64 v[246:247], v[246:247], 0, s[46:47]
	v_add_f32_e32 v127, 0x41800000, v160
	v_cmp_gt_f32_e32 vcc, v126, v127
	s_cbranch_vccnz .Lfox_resc1
.Lfox_resc_ret1:
	s_waitcnt lgkmcnt(7)
	v_mfma_f32_32x32x16_bf16 v[46:61], v[190:193], v[0:3], v[46:61]
	ds_read_b64_tr_b16 v[190:191], v159 offset:34816
	ds_read_b64_tr_b16 v[192:193], v159 offset:35328
	v_sub_f32_e32 v78, v78, v160
	v_sub_f32_e32 v79, v79, v160
	v_sub_f32_e32 v80, v80, v160
	v_sub_f32_e32 v81, v81, v160
	v_sub_f32_e32 v82, v82, v160
	v_sub_f32_e32 v83, v83, v160
	v_sub_f32_e32 v84, v84, v160
	v_sub_f32_e32 v85, v85, v160
	v_exp_f32_e32 v78, v78
	v_exp_f32_e32 v79, v79
	v_exp_f32_e32 v80, v80
	v_exp_f32_e32 v81, v81
	s_waitcnt lgkmcnt(8)
	v_mfma_f32_32x32x16_bf16 v[62:77], v[194:197], v[0:3], v[62:77]
	ds_read_b64_tr_b16 v[194:195], v159 offset:38912
	ds_read_b64_tr_b16 v[196:197], v159 offset:39424
	v_exp_f32_e32 v82, v82
	v_exp_f32_e32 v83, v83
	v_exp_f32_e32 v84, v84
	v_exp_f32_e32 v85, v85
	v_add_f32_e32 v122, v78, v79
	v_add_f32_e32 v123, v80, v81
	v_add_f32_e32 v122, v122, v82
	v_add_f32_e32 v123, v123, v83
	v_add_f32_e32 v122, v122, v84
	v_add_f32_e32 v123, v123, v85
	v_cvt_pk_bf16_f32 v226, v78, v79
	v_cvt_pk_bf16_f32 v227, v80, v81
	s_waitcnt lgkmcnt(9)
	v_mfma_f32_32x32x16_bf16 v[46:61], v[198:201], v[4:7], v[46:61]
	ds_read_b64_tr_b16 v[198:199], v159 offset:35840
	ds_read_b64_tr_b16 v[200:201], v159 offset:36352
	v_cvt_pk_bf16_f32 v228, v82, v83
	v_cvt_pk_bf16_f32 v229, v84, v85
	v_sub_f32_e32 v86, v86, v160
	v_sub_f32_e32 v87, v87, v160
	v_sub_f32_e32 v88, v88, v160
	v_sub_f32_e32 v89, v89, v160
	v_sub_f32_e32 v90, v90, v160
	v_sub_f32_e32 v91, v91, v160
	v_sub_f32_e32 v92, v92, v160
	v_sub_f32_e32 v93, v93, v160
	v_exp_f32_e32 v86, v86
	s_waitcnt lgkmcnt(10)
	v_mfma_f32_32x32x16_bf16 v[62:77], v[202:205], v[4:7], v[62:77]
	ds_read_b64_tr_b16 v[202:203], v159 offset:39936
	ds_read_b64_tr_b16 v[204:205], v159 offset:40448
	v_exp_f32_e32 v87, v87
	v_exp_f32_e32 v88, v88
	v_exp_f32_e32 v89, v89
	v_exp_f32_e32 v90, v90
	v_exp_f32_e32 v91, v91
	v_exp_f32_e32 v92, v92
	v_exp_f32_e32 v93, v93
	v_add_f32_e32 v122, v122, v86
	v_add_f32_e32 v123, v123, v87
	v_add_f32_e32 v122, v122, v88
	v_add_f32_e32 v123, v123, v89
	s_waitcnt lgkmcnt(11)
	v_mfma_f32_32x32x16_bf16 v[46:61], v[206:209], v[8:11], v[46:61]
	ds_read_b64_tr_b16 v[206:207], v159 offset:36864
	ds_read_b64_tr_b16 v[208:209], v159 offset:37376
	v_add_f32_e32 v122, v122, v90
	v_add_f32_e32 v123, v123, v91
	v_add_f32_e32 v122, v122, v92
	v_add_f32_e32 v123, v123, v93
	v_cvt_pk_bf16_f32 v230, v86, v87
	v_cvt_pk_bf16_f32 v231, v88, v89
	v_cvt_pk_bf16_f32 v232, v90, v91
	v_cvt_pk_bf16_f32 v233, v92, v93
	v_sub_f32_e32 v94, v94, v160
	v_sub_f32_e32 v95, v95, v160
	v_sub_f32_e32 v96, v96, v160
	s_waitcnt lgkmcnt(12)
	v_mfma_f32_32x32x16_bf16 v[62:77], v[210:213], v[8:11], v[62:77]
	ds_read_b64_tr_b16 v[210:211], v159 offset:40960
	ds_read_b64_tr_b16 v[212:213], v159 offset:41472
	v_sub_f32_e32 v97, v97, v160
	v_sub_f32_e32 v98, v98, v160
	v_sub_f32_e32 v99, v99, v160
	v_sub_f32_e32 v100, v100, v160
	v_sub_f32_e32 v101, v101, v160
	v_exp_f32_e32 v94, v94
	v_exp_f32_e32 v95, v95
	v_exp_f32_e32 v96, v96
	v_exp_f32_e32 v97, v97
	v_exp_f32_e32 v98, v98
	v_exp_f32_e32 v99, v99
	s_waitcnt lgkmcnt(13)
	v_mfma_f32_32x32x16_bf16 v[46:61], v[214:217], v[110:113], v[46:61]
	ds_read_b64_tr_b16 v[214:215], v159 offset:37888
	ds_read_b64_tr_b16 v[216:217], v159 offset:38400
	v_exp_f32_e32 v100, v100
	v_exp_f32_e32 v101, v101
	v_add_f32_e32 v122, v122, v94
	v_add_f32_e32 v123, v123, v95
	v_add_f32_e32 v122, v122, v96
	v_add_f32_e32 v123, v123, v97
	v_add_f32_e32 v122, v122, v98
	v_add_f32_e32 v123, v123, v99
	v_add_f32_e32 v122, v122, v100
	v_add_f32_e32 v123, v123, v101
	v_cvt_pk_bf16_f32 v234, v94, v95
	s_waitcnt lgkmcnt(14)
	v_mfma_f32_32x32x16_bf16 v[62:77], v[222:225], v[110:113], v[62:77]
	s_waitcnt lgkmcnt(13)
	ds_read_b64_tr_b16 v[222:223], v159 offset:41984
	ds_read_b64_tr_b16 v[224:225], v159 offset:42496
	v_cvt_pk_bf16_f32 v235, v96, v97
	v_cvt_pk_bf16_f32 v236, v98, v99
	v_cvt_pk_bf16_f32 v237, v100, v101
	v_sub_f32_e32 v102, v102, v160
	v_sub_f32_e32 v103, v103, v160
	v_sub_f32_e32 v104, v104, v160
	v_sub_f32_e32 v105, v105, v160
	v_sub_f32_e32 v106, v106, v160
	v_sub_f32_e32 v107, v107, v160
	v_sub_f32_e32 v108, v108, v160
	v_sub_f32_e32 v109, v109, v160
	s_waitcnt lgkmcnt(8)
	s_waitcnt vmcnt(0)
	ds_write_b128 v162, v[114:117] offset:13312
	s_and_saveexec_b64 s[12:13], s[6:7]
	s_cbranch_execz .Lfox_nocw1
	v_xor_b32_e32 v152, 0x80000000, v152
	ds_write_b32 v154, v152 offset:43264
.Lfox_nocw1:
	s_or_b64 exec, exec, s[12:13]
	ds_write_b128 v155, v[118:121] offset:26624
	v_exp_f32_e32 v102, v102
	v_exp_f32_e32 v103, v103
	v_exp_f32_e32 v104, v104
	v_exp_f32_e32 v105, v105
	v_exp_f32_e32 v106, v106
	v_exp_f32_e32 v107, v107
	v_exp_f32_e32 v108, v108
	v_exp_f32_e32 v109, v109
	v_add_f32_e32 v122, v122, v102
	v_add_f32_e32 v123, v123, v103
	v_add_f32_e32 v122, v122, v104
	v_add_f32_e32 v123, v123, v105
	v_add_f32_e32 v122, v122, v106
	v_add_f32_e32 v123, v123, v107
	v_add_f32_e32 v122, v122, v108
	v_add_f32_e32 v123, v123, v109
	v_cvt_pk_bf16_f32 v238, v102, v103
	v_cvt_pk_bf16_f32 v239, v104, v105
	v_cvt_pk_bf16_f32 v240, v106, v107
	v_cvt_pk_bf16_f32 v241, v108, v109
	v_add_f32_e32 v122, v122, v123
	v_add_f32_e32 v161, v161, v122
	s_waitcnt lgkmcnt(0)
	s_barrier
	ds_read_b128 v[78:81], v158 offset:43264
	ds_read_b128 v[82:85], v158 offset:43296
	ds_read_b128 v[86:89], v158 offset:43328
	ds_read_b128 v[90:93], v158 offset:43360
	ds_read_b128 v[94:97], v158 offset:43392
	ds_read_b128 v[98:101], v158 offset:43424
	ds_read_b128 v[102:105], v158 offset:43456
	ds_read_b128 v[106:109], v158 offset:43488
	v_mfma_f32_32x32x16_bf16 v[14:29], v[190:193], v[226:229], v[14:29]
	ds_read_b128 v[190:193], v218 offset:13312
	v_max3_f32 v124, v46, v47, v48
	v_max3_f32 v125, v49, v50, v51
	v_max3_f32 v124, v124, v52, v53
	v_mfma_f32_32x32x16_bf16 v[30:45], v[194:197], v[226:229], v[30:45]
	ds_read_b128 v[194:197], v218 offset:17920
	global_load_dwordx4 v[114:117], v[244:245], off
	s_and_saveexec_b64 s[12:13], s[6:7]
	s_cbranch_execz .Lfox_nock1
	global_load_dword v152, v[250:251], off offset:256
.Lfox_nock1:
	s_or_b64 exec, exec, s[12:13]
	global_load_dwordx4 v[118:121], v[248:249], off
	v_max3_f32 v125, v125, v54, v55
	v_max3_f32 v124, v124, v56, v57
	v_max3_f32 v125, v125, v58, v59
	v_mfma_f32_32x32x16_bf16 v[14:29], v[198:201], v[230:233], v[14:29]
	ds_read_b128 v[198:201], v218 offset:13344
	v_max3_f32 v124, v124, v60, v61
	v_max3_f32 v125, v125, v62, v63
	v_max3_f32 v124, v124, v64, v65
	v_mfma_f32_32x32x16_bf16 v[30:45], v[202:205], v[230:233], v[30:45]
	ds_read_b128 v[202:205], v218 offset:17952
	v_max3_f32 v125, v125, v66, v67
	v_max3_f32 v124, v124, v68, v69
	v_max3_f32 v125, v125, v70, v71
	v_mfma_f32_32x32x16_bf16 v[14:29], v[206:209], v[234:237], v[14:29]
	ds_read_b128 v[206:209], v218 offset:13376
	v_max3_f32 v124, v124, v72, v73
	v_max3_f32 v125, v125, v74, v75
	v_mfma_f32_32x32x16_bf16 v[30:45], v[210:213], v[234:237], v[30:45]
	ds_read_b128 v[210:213], v218 offset:17984
	v_max3_f32 v124, v124, v76, v77
	v_max_f32_e32 v124, v124, v125
	v_mfma_f32_32x32x16_bf16 v[14:29], v[214:217], v[238:241], v[14:29]
	ds_read_b128 v[214:217], v218 offset:13408
	v_mov_b32_e32 v125, v124
	s_nop 1
	v_mfma_f32_32x32x16_bf16 v[30:45], v[222:225], v[238:241], v[30:45]
	s_waitcnt lgkmcnt(14)
	ds_read_b128 v[222:225], v218 offset:18016
	v_permlane32_swap_b32_e32 v124, v125
	v_max_f32_e32 v126, v124, v125
	v_lshl_add_u64 v[244:245], v[244:245], 0, s[46:47]
	v_lshl_add_u64 v[248:249], v[248:249], 0, s[46:47]
	v_lshl_add_u64 v[250:251], v[250:251], 0, s[48:49]
	s_add_i32 s10, s10, 2
	s_add_i32 s12, s10, 2
	s_cmp_ge_i32 s12, s35
	s_cbranch_scc0 .Lfox_loop
	s_waitcnt vmcnt(0) lgkmcnt(0)
	s_barrier
	s_branch .LBB0_670
.Lfox_resc0:
	s_nop 15
	v_max_f32_e32 v127, v160, v126
	v_sub_f32_e32 v128, v160, v127
	v_exp_f32_e32 v128, v128
	v_mov_b32_e32 v160, v127
	v_mul_f32_e32 v161, v161, v128
	v_mul_f32_e32 v14, v14, v128
	v_mul_f32_e32 v15, v15, v128
	v_mul_f32_e32 v16, v16, v128
	v_mul_f32_e32 v17, v17, v128
	v_mul_f32_e32 v18, v18, v128
	v_mul_f32_e32 v19, v19, v128
	v_mul_f32_e32 v20, v20, v128
	v_mul_f32_e32 v21, v21, v128
	v_mul_f32_e32 v22, v22, v128
	v_mul_f32_e32 v23, v23, v128
	v_mul_f32_e32 v24, v24, v128
	v_mul_f32_e32 v25, v25, v128
	v_mul_f32_e32 v26, v26, v128
	v_mul_f32_e32 v27, v27, v128
	v_mul_f32_e32 v28, v28, v128
	v_mul_f32_e32 v29, v29, v128
	v_mul_f32_e32 v30, v30, v128
	v_mul_f32_e32 v31, v31, v128
	v_mul_f32_e32 v32, v32, v128
	v_mul_f32_e32 v33, v33, v128
	v_mul_f32_e32 v34, v34, v128
	v_mul_f32_e32 v35, v35, v128
	v_mul_f32_e32 v36, v36, v128
	v_mul_f32_e32 v37, v37, v128
	v_mul_f32_e32 v38, v38, v128
	v_mul_f32_e32 v39, v39, v128
	v_mul_f32_e32 v40, v40, v128
	v_mul_f32_e32 v41, v41, v128
	v_mul_f32_e32 v42, v42, v128
	v_mul_f32_e32 v43, v43, v128
	v_mul_f32_e32 v44, v44, v128
	v_mul_f32_e32 v45, v45, v128
	s_branch .Lfox_resc_ret0
